# Strategy 4: one static s_setprio 1 for waves 4-7 across the attention tile loop (reset after the loop)
# speedup vs baseline: 1.0029x; 1.0001x over previous
; DI void attn_unit(const bf16_t* z, const bf16_t* VT, bf16_t* Y, const float* subg, ldsp lds, int tid, int b, int h, int qb, float lam, float ns, float oscale, int win) {
;     const int w = __builtin_amdgcn_readfirstlane(tid >> 6), lane = tid & 63, fr = lane & 15, fq = lane >> 4;
;     const int comp = w & 1, g = w >> 1;
;     const int q0 = qb * 128 + g * 32, nt = 2 * qb + 2, wlast = 2 * qb + (g >> 1);
;     const int jstart = max(0, (qb * 128 - win) >> 6), wfirst = max(0, (q0 - win) >> 6);
;     bf16x8 qf[2][2];
; #pragma unroll
;     for (int qt = 0; qt < 2; ++qt)
; #pragma unroll
;         for (int ks = 0; ks < 2; ++ks) qf[qt][ks] = *(const bf16x8*)(z + (size_t)(b * SEQ + q0 + 16 * qt + fr) * ZLD + C_DQ + h * 128 + comp * 64 + 32 * ks + 8 * fq);
;     f32x4 O[8][2];
; #pragma unroll
;     for (int e = 0; e < 8; ++e)
; #pragma unroll
;         for (int qt = 0; qt < 2; ++qt) O[e][qt] = (f32x4){0.f, 0.f, 0.f, 0.f};
;     float ls0 = 0.f, ls1 = 0.f;
;     const float tq0 = (float)(q0 + fr), tq1 = tq0 + 16.0f;
;     const int kr = 4 * w + (lane >> 4), vr = 8 * w + (lane >> 3);
;     const bf16_t* kg = z + (size_t)(b * SEQ + kr) * ZLD + C_DK + h * 128 + (((lane & 15) ^ (kr & 15)) * 8);
;     const bf16_t* vg = VT + (size_t)((b * 4 + h) * 128 + vr) * SEQ + (((lane & 7) ^ ((vr >> 1) & 7)) * 8);
;     ...
;     int koff[2], voff[2];
; #pragma unroll
;     for (int ks = 0; ks < 2; ++ks) koff[ks] = fr * 256 + (((comp * 8 + 4 * ks + fq) ^ fr) * 16);
; #pragma unroll
;     for (int m = 0; m < 2; ++m) voff[m] = AT_KT + fr * 128 + (((4 * m + fq) ^ ((fr >> 1) & 7)) * 16);
;     __syncthreads();
;     AT_DMA(jstart, jstart & 1);
;     asm volatile("s_waitcnt vmcnt(0)" ::: "memory");
;     __syncthreads();
; __global__ void __launch_bounds__(512, 2) hybrid_fwd(Args a) {
;     ...
;                         const int r = 63 - (xq & 1) - 2 * (idx >> 2), h = idx & 3, b = xq >> 1;
;                         const float slope = exp2f(-2.0f * (float)(h + 1));
;                         const float wf = (104.0f + 2.0f * smax) / slope;
;                         const int win = wf < 16384.0f ? (int)wf + 1 : 16384;
.LBB0_410:
	s_andn2_b64 vcc, exec, s[0:1]
	s_cbranch_vccnz .LBB0_401
	s_lshr_b32 s12, s28, 5
	s_sub_i32 s12, 3, s12
	s_not_b32 s0, s12
	s_lshl_b32 s0, s0, 1
	v_ldexp_f32 v85, 1.0, s0
	v_div_scale_f32 v0, s[0:1], v85, v85, v175
	v_rcp_f32_e32 v1, v0
	v_div_scale_f32 v2, vcc, v175, v85, v175
	s_and_b32 s0, s28, 31
	v_fma_f32 v3, -v0, v1, 1.0
	v_fmac_f32_e32 v1, v3, v1
	v_mul_f32_e32 v3, v2, v1
	v_fma_f32 v4, -v0, v3, v2
	v_fmac_f32_e32 v3, v4, v1
	v_fma_f32 v0, -v0, v3, v2
	v_div_fmas_f32 v0, v0, v1, v3
	v_div_fixup_f32 v0, v0, v85, v175
	v_cvt_i32_f32_e32 v1, v0
	s_lshl_b32 s0, s0, 1
	s_sub_i32 s14, s84, s0
	s_mov_b32 s0, 0x46800000
	v_cmp_gt_f32_e32 vcc, s0, v0
	v_readfirstlane_b32 s0, v80
	s_ashr_i32 s8, s0, 7
	v_add_u32_e32 v1, 1, v1
	s_lshl_b32 s6, s14, 7
	s_lshl_b32 s1, s8, 5
	v_cndmask_b32_e32 v86, v211, v1, vcc
	s_add_i32 s1, s1, s6
	v_sub_u32_e32 v0, s6, v86
	s_add_i32 s6, s1, s85
	s_ashr_i32 s15, s0, 6
	v_ashrrev_i32_e32 v4, 6, v0
	v_or_b32_e32 v120, s6, v81
	v_mov_b64_e32 v[0:1], s[70:71]
	s_and_b32 s9, s15, 1
	v_mad_i64_i32 v[2:3], s[10:11], v120, s97, v[0:1]
	s_lshl_b32 s30, s12, 8
	v_lshl_add_u64 v[2:3], v[2:3], 0, s[30:31]
	s_lshl_b32 s10, s9, 7
	s_mov_b32 s11, s31
	v_lshl_add_u64 v[2:3], v[2:3], 0, s[10:11]
	v_and_b32_e32 v156, 48, v80
	v_lshl_add_u64 v[2:3], v[2:3], 0, v[156:157]
	v_or_b32_e32 v118, 16, v120
	s_lshl_b32 s6, s12, 7
	global_load_dwordx4 v[56:59], v[2:3], off offset:1536
	global_load_dwordx4 v[60:63], v[2:3], off offset:1600
	v_mad_i64_i32 v[2:3], s[12:13], v118, s97, v[0:1]
	v_lshl_add_u64 v[2:3], v[2:3], 0, s[30:31]
	v_lshl_add_u64 v[2:3], v[2:3], 0, s[10:11]
	v_lshl_add_u64 v[2:3], v[2:3], 0, v[156:157]
	s_lshl_b32 s12, s15, 2
	global_load_dwordx4 v[64:67], v[2:3], off offset:1536
	global_load_dwordx4 v[68:71], v[2:3], off offset:1600
	v_or_b32_e32 v2, s12, v177
	v_add_u32_e32 v2, s85, v2
	v_bfe_u32 v3, v80, 3, 3
	v_mad_i64_i32 v[0:1], s[10:11], v2, s97, v[0:1]
	v_lshl_or_b32 v5, s15, 3, v3
	v_bitop3_b32 v6, s12, v80, v177 bitop3:0x36
	s_or_b32 s10, s6, s86
	v_add_u32_e32 v2, s10, v5
	v_lshrrev_b32_e32 v5, 1, v5
	v_lshlrev_b32_e32 v6, 4, v6
	v_max_i32_e32 v84, 0, v4
	v_xor_b32_e32 v5, v5, v80
	v_lshl_add_u64 v[0:1], v[0:1], 0, s[30:31]
	v_and_b32_e32 v156, 0xf0, v6
	v_ashrrev_i32_e32 v3, 31, v2
	v_lshl_add_u64 v[122:123], v[0:1], 0, v[156:157]
	v_lshlrev_b32_e32 v0, 4, v5
	v_lshlrev_b32_e32 v82, 6, v84
	v_lshlrev_b64 v[2:3], 14, v[2:3]
	v_and_b32_e32 v156, 0x70, v0
	v_mad_u64_u32 v[0:1], s[10:11], v82, s97, v[122:123]
	v_lshl_add_u64 v[2:3], s[62:63], 0, v[2:3]
	v_lshlrev_b32_e32 v83, 15, v84
	s_lshl_b32 s10, s15, 10
	v_lshl_add_u64 v[124:125], v[2:3], 0, v[156:157]
	v_and_b32_e32 v2, 0x8000, v83
	s_add_i32 s10, s10, 0
	v_add_u32_e32 v2, s10, v2
	v_lshl_add_u64 v[0:1], v[0:1], 0, s[18:19]
	v_readfirstlane_b32 s11, v2
	s_mov_b32 m0, s11
	s_barrier
	global_load_lds_dwordx4 v[0:1], off
	v_or_b32_e32 v0, 32, v82
	v_add_u32_e32 v3, 0x2000, v2
	v_mad_u64_u32 v[0:1], s[12:13], v0, s97, v[122:123]
	v_readfirstlane_b32 s11, v3
	v_add_u32_e32 v3, 0x4000, v2
	v_lshl_add_u64 v[0:1], v[0:1], 0, s[18:19]
	s_mov_b32 m0, s11
	v_lshlrev_b32_e32 v156, 7, v84
	v_readfirstlane_b32 s11, v3
	s_mov_b64 s[12:13], 0x100000
	v_add_u32_e32 v2, 0x6000, v2
	global_load_lds_dwordx4 v[0:1], off
	v_lshl_add_u64 v[0:1], v[124:125], 0, v[156:157]
	s_mov_b32 m0, s11
	v_lshl_add_u64 v[126:127], v[124:125], 0, s[12:13]
	v_readfirstlane_b32 s11, v2
	global_load_lds_dwordx4 v[0:1], off
	v_lshl_add_u64 v[0:1], v[126:127], 0, v[156:157]
	s_mov_b32 m0, s11
	s_lshl_b32 s12, s14, 1
	global_load_lds_dwordx4 v[0:1], off
	s_waitcnt vmcnt(0)
	s_add_i32 s11, s12, 2
	v_mov_b32_e32 v129, 0
	v_cmp_gt_i32_e32 vcc, s11, v4
	v_mov_b32_e32 v128, v129
	v_mov_b32_e32 v3, v129
	v_mov_b32_e32 v2, v129
	v_mov_b32_e32 v1, v129
	v_mov_b32_e32 v0, v129
	v_mov_b32_e32 v7, v129
	v_mov_b32_e32 v6, v129
	v_mov_b32_e32 v5, v129
	v_mov_b32_e32 v4, v129
	v_mov_b32_e32 v11, v129
	v_mov_b32_e32 v10, v129
	v_mov_b32_e32 v9, v129
	v_mov_b32_e32 v8, v129
	v_mov_b32_e32 v27, v129
	v_mov_b32_e32 v26, v129
	v_mov_b32_e32 v25, v129
	v_mov_b32_e32 v24, v129
	v_mov_b32_e32 v75, v129
	v_mov_b32_e32 v74, v129
	v_mov_b32_e32 v73, v129
	v_mov_b32_e32 v72, v129
	v_mov_b32_e32 v79, v129
	v_mov_b32_e32 v78, v129
	v_mov_b32_e32 v77, v129
	v_mov_b32_e32 v76, v129
	v_mov_b32_e32 v55, v129
	v_mov_b32_e32 v54, v129
	v_mov_b32_e32 v53, v129
	v_mov_b32_e32 v52, v129
	v_mov_b32_e32 v51, v129
	v_mov_b32_e32 v50, v129
	v_mov_b32_e32 v49, v129
	v_mov_b32_e32 v48, v129
	v_mov_b32_e32 v47, v129
	v_mov_b32_e32 v46, v129
	v_mov_b32_e32 v45, v129
	v_mov_b32_e32 v44, v129
	v_mov_b32_e32 v43, v129
	v_mov_b32_e32 v42, v129
	v_mov_b32_e32 v41, v129
	v_mov_b32_e32 v40, v129
	v_mov_b32_e32 v39, v129
	v_mov_b32_e32 v38, v129
	v_mov_b32_e32 v37, v129
	v_mov_b32_e32 v36, v129
	v_mov_b32_e32 v35, v129
	v_mov_b32_e32 v34, v129
	v_mov_b32_e32 v33, v129
	v_mov_b32_e32 v32, v129
	v_mov_b32_e32 v31, v129
	v_mov_b32_e32 v30, v129
	v_mov_b32_e32 v29, v129
	v_mov_b32_e32 v28, v129
	v_mov_b32_e32 v23, v129
	v_mov_b32_e32 v22, v129
	v_mov_b32_e32 v21, v129
	v_mov_b32_e32 v20, v129
	v_mov_b32_e32 v19, v129
	v_mov_b32_e32 v18, v129
	v_mov_b32_e32 v17, v129
	v_mov_b32_e32 v16, v129
	v_mov_b32_e32 v15, v129
	v_mov_b32_e32 v14, v129
	v_mov_b32_e32 v13, v129
	v_mov_b32_e32 v12, v129
	s_waitcnt vmcnt(0) lgkmcnt(0)
	s_barrier
; DI void attn_unit(const bf16_t* z, const bf16_t* VT, bf16_t* Y, const float* subg, ldsp lds, int tid, int b, int h, int qb, float lam, float ns, float oscale, int win) {
;     ...
;     const int q0 = qb * 128 + g * 32, nt = 2 * qb + 2, wlast = 2 * qb + (g >> 1);
;     const int jstart = max(0, (qb * 128 - win) >> 6), wfirst = max(0, (q0 - win) >> 6);
;     bf16x8 qf[2][2];
; #pragma unroll
;     for (int qt = 0; qt < 2; ++qt)
; #pragma unroll
;         for (int ks = 0; ks < 2; ++ks) qf[qt][ks] = *(const bf16x8*)(z + (size_t)(b * SEQ + q0 + 16 * qt + fr) * ZLD + C_DQ + h * 128 + comp * 64 + 32 * ks + 8 * fq);
;     f32x4 O[8][2];
; #pragma unroll
;     for (int e = 0; e < 8; ++e)
; #pragma unroll
;         for (int qt = 0; qt < 2; ++qt) O[e][qt] = (f32x4){0.f, 0.f, 0.f, 0.f};
;     float ls0 = 0.f, ls1 = 0.f;
;     const float tq0 = (float)(q0 + fr), tq1 = tq0 + 16.0f;
;     const int kr = 4 * w + (lane >> 4), vr = 8 * w + (lane >> 3);
;     const bf16_t* kg = z + (size_t)(b * SEQ + kr) * ZLD + C_DK + h * 128 + (((lane & 15) ^ (kr & 15)) * 8);
;     const bf16_t* vg = VT + (size_t)((b * 4 + h) * 128 + vr) * SEQ + (((lane & 7) ^ ((vr >> 1) & 7)) * 8);
;     ...
;     int koff[2], voff[2];
; #pragma unroll
;     for (int ks = 0; ks < 2; ++ks) koff[ks] = fr * 256 + (((comp * 8 + 4 * ks + fq) ^ fr) * 16);
; #pragma unroll
;     for (int m = 0; m < 2; ++m) voff[m] = AT_KT + fr * 128 + (((4 * m + fq) ^ ((fr >> 1) & 7)) * 16);
;     __syncthreads();
;     AT_DMA(jstart, jstart & 1);
;     asm volatile("s_waitcnt vmcnt(0)" ::: "memory");
;     __syncthreads();
;     for (int j = jstart; j < nt; ++j) {
;         if (j + 1 < nt) AT_DMA(j + 1, (j + 1) & 1);
;         if (j <= wlast && j >= wfirst) {
	s_and_saveexec_b64 s[28:29], vcc
	s_cbranch_execz .LBB0_419
	s_ashr_i32 s0, s0, 8
	s_add_i32 s12, s0, s12
	v_or_b32_e32 v1, s1, v81
	s_lshl_b32 s0, s9, 3
	v_sub_u32_e32 v0, s1, v86
	v_cvt_f32_i32_e32 v121, v1
	v_or_b32_e32 v1, s0, v177
	v_bitop3_b32 v1, v1, v81, 4 bitop3:0x36
	v_ashrrev_i32_e32 v182, 6, v0
	v_lshrrev_b32_e32 v0, 1, v80
	v_lshlrev_b32_e32 v181, 4, v1
	v_bfe_u32 v1, v80, 1, 3
	v_bitop3_b32 v0, v177, v0, 7 bitop3:0x78
	v_bitop3_b32 v2, s0, v81, v177 bitop3:0x36
	v_lshlrev_b32_e32 v184, 4, v0
	v_bitop3_b32 v0, v177, v1, 4 bitop3:0x36
	v_mov_b32_e32 v12, 0
	v_mul_f32_e32 v119, 0xbfb8aa3b, v85
	v_lshlrev_b32_e32 v179, 8, v81
	v_lshlrev_b32_e32 v180, 4, v2
	v_lshlrev_b32_e32 v183, 7, v81
	v_lshlrev_b32_e32 v185, 4, v0
	v_add_f32_e32 v186, 0x41800000, v121
	v_lshlrev_b32_e32 v187, 2, v177
	s_mov_b64 s[74:75], 0
	v_mov_b32_e32 v13, v12
	v_mov_b32_e32 v14, v12
	v_mov_b32_e32 v15, v12
	v_mov_b32_e32 v16, v12
	v_mov_b32_e32 v17, v12
	v_mov_b32_e32 v18, v12
	v_mov_b32_e32 v19, v12
	v_mov_b32_e32 v20, v12
	v_mov_b32_e32 v21, v12
	v_mov_b32_e32 v22, v12
	v_mov_b32_e32 v23, v12
	v_mov_b32_e32 v28, v12
	v_mov_b32_e32 v29, v12
	v_mov_b32_e32 v30, v12
	v_mov_b32_e32 v31, v12
	v_mov_b32_e32 v32, v12
	v_mov_b32_e32 v33, v12
	v_mov_b32_e32 v34, v12
	v_mov_b32_e32 v35, v12
	v_mov_b32_e32 v36, v12
	v_mov_b32_e32 v37, v12
	v_mov_b32_e32 v38, v12
	v_mov_b32_e32 v39, v12
	v_mov_b32_e32 v40, v12
	v_mov_b32_e32 v41, v12
	v_mov_b32_e32 v42, v12
	v_mov_b32_e32 v43, v12
	v_mov_b32_e32 v44, v12
	v_mov_b32_e32 v45, v12
	v_mov_b32_e32 v46, v12
	v_mov_b32_e32 v47, v12
	v_mov_b32_e32 v48, v12
	v_mov_b32_e32 v49, v12
	v_mov_b32_e32 v50, v12
	v_mov_b32_e32 v51, v12
	v_mov_b32_e32 v52, v12
	v_mov_b32_e32 v53, v12
	v_mov_b32_e32 v54, v12
	v_mov_b32_e32 v55, v12
	v_mov_b32_e32 v76, v12
	v_mov_b32_e32 v77, v12
	v_mov_b32_e32 v78, v12
	v_mov_b32_e32 v79, v12
	v_mov_b32_e32 v72, v12
	v_mov_b32_e32 v73, v12
	v_mov_b32_e32 v74, v12
	v_mov_b32_e32 v75, v12
	v_mov_b32_e32 v24, v12
	v_mov_b32_e32 v25, v12
	v_mov_b32_e32 v26, v12
	v_mov_b32_e32 v27, v12
	v_mov_b32_e32 v8, v12
	v_mov_b32_e32 v9, v12
	v_mov_b32_e32 v10, v12
	v_mov_b32_e32 v11, v12
	v_mov_b32_e32 v4, v12
	v_mov_b32_e32 v5, v12
	v_mov_b32_e32 v6, v12
	v_mov_b32_e32 v7, v12
	v_mov_b32_e32 v0, v12
	v_mov_b32_e32 v1, v12
	v_mov_b32_e32 v2, v12
	v_mov_b32_e32 v3, v12
	v_mov_b32_e32 v128, v12
	v_mov_b32_e32 v129, v12
	v_readfirstlane_b32 s74, v84
	v_readfirstlane_b32 s75, v182
	v_add_u32_e32 v130, v179, v180
	v_add_u32_e32 v131, v179, v181
	v_add_u32_e32 v132, v183, v184
	v_add_u32_e32 v133, v183, v185
	v_add_u32_e32 v132, 0x4000, v132
	v_add_u32_e32 v133, 0x4000, v133
	s_mov_b32 s43, s74
	s_max_i32 s75, s75, s74
	s_add_i32 s42, s11, -1
	s_min_i32 s42, s42, s12
	s_add_i32 s74, s74, -1
	s_and_b32 s101, s43, 1
	s_cmp_ge_u32 s10, 0x1000
	s_cbranch_scc0 .Lat_noprio
	s_setprio 1
.Lat_noprio:
.Lat_loop:
	s_lshl_b32 s1, s101, 15
	s_add_i32 s14, s101, 1
	s_cmp_ge_i32 s14, 2
	s_cselect_b32 s0, 2, 0
	s_sub_i32 s14, s14, s0
	s_lshl_b32 s14, s14, 15
	v_add_u32_e32 v134, s1, v130
	v_add_u32_e32 v135, s1, v131
	v_add_u32_e32 v138, s14, v132
	v_add_u32_e32 v139, s14, v133
	s_add_i32 s0, s74, 1
	s_cmp_ge_i32 s0, s75
	s_cselect_b32 s1, 1, 0
	s_cmp_le_i32 s0, s42
	s_cselect_b32 s14, 1, 0
	s_and_b32 s1, s1, s14
	s_cmp_ge_i32 s74, s75
	s_cselect_b32 s14, 2, 0
	s_cmp_le_i32 s74, s42
	s_cselect_b32 s15, 2, 0
	s_and_b32 s14, s14, s15
	s_or_b32 s1, s1, s14
	s_cmp_eq_u32 s1, 3
	s_cbranch_scc1 .Lat_both
	s_cmp_eq_u32 s1, 1
	s_cbranch_scc1 .Lat_qk
	s_cmp_eq_u32 s1, 2
	s_cbranch_scc1 .Lat_pv
	s_add_i32 s0, s74, 2
	s_cmp_lt_i32 s0, s11
	s_cbranch_scc0 .Lat_nok_n
	s_mul_i32 s14, s0, 0x70000
	s_add_i32 s14, s14, 0xa00
	s_mov_b32 s15, 0
	v_lshl_add_u64 v[214:215], v[122:123], 0, s[14:15]
	s_add_i32 s1, s101, 1
	s_cmp_ge_i32 s1, 2
	s_cselect_b32 s0, 2, 0
	s_sub_i32 s1, s1, s0
	s_lshl_b32 s1, s1, 15
	s_add_i32 s1, s1, s10
	s_mov_b32 m0, s1
	s_add_i32 s14, s14, 0x38000
	global_load_lds_dwordx4 v[214:215], off
	v_lshl_add_u64 v[80:81], v[122:123], 0, s[14:15]
	s_add_i32 m0, s1, 0x2000
	s_nop 0
	global_load_lds_dwordx4 v[80:81], off

; DI void attn_unit(const bf16_t* z, const bf16_t* VT, bf16_t* Y, const float* subg, ldsp lds, int tid, int b, int h, int qb, float lam, float ns, float oscale, int win) {
;     ...
;         asm volatile("s_waitcnt vmcnt(0)" ::: "memory");
;         __syncthreads();
;     }
;     ...
;     ls0 += __shfl_xor(ls0, 16); ls0 += __shfl_xor(ls0, 32);
.Lat_exit:
	s_setprio 0
